# mLSTM-prep gate block: the two 64-lane prefix scans and the wave max use DPP row-shift/row-bcast scans plus v_readlane instead of 19 ds_bpermute round trips
# speedup vs baseline: 1.0147x; 1.0014x over previous
.LBB0_630:
	v_cndmask_b32_e64 v0, v130, v126, s[70:71]
	s_movk_i32 s1, 0x68
	v_mad_u32_u24 v0, v0, s1, v100
	v_lshl_add_u32 v0, v0, 1, v124
	s_waitcnt lgkmcnt(0)
	s_barrier
	ds_write_b128 v0, v[4:7]
	ds_write_b128 v0, v[8:11] offset:13312
	ds_write_b128 v0, v[16:19] offset:26624
	v_cndmask_b32_e64 v0, v131, v128, s[70:71]
	v_mad_u32_u24 v0, v0, s1, v102
	v_lshl_add_u32 v0, v0, 1, v124
	ds_write_b128 v0, v[12:15]
	ds_write_b128 v0, v[20:23] offset:13312
	ds_write_b128 v0, v[28:31] offset:26624
	v_cndmask_b32_e64 v0, v132, v129, s[70:71]
	v_mad_u32_u24 v0, v0, s1, v104
	v_lshl_add_u32 v0, v0, 1, v124
	ds_write_b128 v0, v[24:27]
	ds_write_b128 v0, v[32:35] offset:13312
	ds_write_b128 v0, v[36:39] offset:26624
	s_and_saveexec_b64 s[96:97], s[42:43]
	s_cbranch_execz .LBB0_633
	s_lshl_b32 s1, s76, 2
	s_cmp_eq_u32 s76, 0
	s_cselect_b64 vcc, -1, 0
	s_nop 0
	v_cndmask_b32_e32 v0, v235, v234, vcc
	v_cndmask_b32_e32 v2, v237, v236, vcc
	v_cndmask_b32_e64 v78, v101, v117, s[70:71]
	v_lshlrev_b32_e32 v78, 16, v78
	s_mov_b64 vcc, s[70:71]
	v_and_b32_e32 v79, 64, v209
	v_add_u32_e32 v80, -1, v209
	v_add_u32_e32 v81, -2, v209
	v_cndmask_b32_sdwa v76, v105, v103, vcc dst_sel:WORD_1 dst_unused:UNUSED_PAD src0_sel:DWORD src1_sel:DWORD
	v_cmp_lt_i32_e32 vcc, v80, v79
	v_add_u32_e32 v82, -4, v209
	v_add_u32_e32 v83, -8, v209
	v_cndmask_b32_e32 v80, v80, v209, vcc
	v_cmp_lt_i32_e32 vcc, v81, v79
	v_add_u32_e32 v84, -16, v209
	v_subrev_u32_e32 v85, 32, v209
	v_cndmask_b32_e32 v81, v81, v209, vcc
	v_cmp_lt_i32_e32 vcc, v82, v79
	v_cndmask_b32_e64 v77, v133, v123, s[70:71]
	v_xor_b32_e32 v87, 32, v209
	v_cndmask_b32_e32 v82, v82, v209, vcc
	v_xor_b32_e32 v88, 16, v209
	v_xor_b32_e32 v89, 8, v209
	v_xor_b32_e32 v90, 4, v209
	v_xor_b32_e32 v3, 2, v209
	v_lshl_or_b32 v86, v209, 2, v224
	v_xor_b32_e32 v91, 1, v209
	s_lshl_b64 s[38:39], s[76:77], 2
	s_nop 0
	v_add_f32_e32 v0, v0, v78
	v_mul_f32_e64 v78, |v0|, s36
	v_exp_f32_e32 v78, v78
	v_min_f32_e32 v0, 0, v0
	v_add_f32_e32 v78, 1.0, v78
	v_cmp_gt_f32_e32 vcc, s5, v78
	s_nop 1
	v_cndmask_b32_e64 v92, 0, 32, vcc
	v_ldexp_f32 v78, v78, v92
	v_log_f32_e32 v78, v78
	v_lshlrev_b32_e32 v92, 2, v80
	v_cndmask_b32_e32 v80, 0, v223, vcc
	v_mul_f32_e32 v93, 0x3f317217, v78
	v_fma_f32 v93, v78, s75, -v93
	v_fmac_f32_e32 v93, 0x3377d1cf, v78
	v_fmac_f32_e32 v93, 0x3f317217, v78
	v_cmp_lt_f32_e64 vcc, |v78|, s33
	s_nop 1
	v_cndmask_b32_e32 v78, v78, v93, vcc
	v_sub_f32_e32 v78, v78, v80
	v_sub_f32_e32 v0, v0, v78
	v_or_b32_e32 v80, v77, v171
	v_ashrrev_i32_e32 v81, 31, v80
	v_lshlrev_b64 v[80:81], 3, v[80:81]
	v_or3_b32 v81, v81, s39, 0
	v_or3_b32 v80, v80, s38, v116
	v_lshl_add_u64 v[84:85], v[80:81], 4, s[12:13]
	s_nop 1
	v_add_f32_dpp v0, v0, v0 row_shr:1 row_mask:0xf bank_mask:0xf
	s_nop 1
	v_add_f32_dpp v0, v0, v0 row_shr:2 row_mask:0xf bank_mask:0xf
	s_nop 1
	v_add_f32_dpp v0, v0, v0 row_shr:4 row_mask:0xf bank_mask:0xf
	s_nop 1
	v_add_f32_dpp v0, v0, v0 row_shr:8 row_mask:0xf bank_mask:0xf
	s_nop 1
	v_add_f32_dpp v0, v0, v0 row_bcast:15 row_mask:0xa bank_mask:0xf
	s_nop 1
	v_add_f32_dpp v0, v0, v0 row_bcast:31 row_mask:0xc bank_mask:0xf
	s_nop 1
	v_mov_b32_e32 v3, v0
	s_nop 1
	v_readlane_b32 s100, v3, 63
	s_nop 3
	v_mov_b32_e32 v77, s100
	v_pk_add_f32 v[78:79], v[2:3], v[76:77]
	v_sub_f32_e32 v0, v77, v3
	v_pk_add_f32 v[82:83], v[78:79], v[0:1] op_sel_hi:[1,0]
	v_sub_f32_e32 v79, v78, v3
	v_mov_b32_e32 v78, v3
	v_mov_b32_e32 v0, v82
	v_mov_b32_e32 v2, v79
	s_nop 1
	v_max_f32_dpp v0, v0, v0 row_shr:1 row_mask:0xf bank_mask:0xf
	v_max_f32_dpp v2, v2, v2 row_shr:1 row_mask:0xf bank_mask:0xf
	s_nop 1
	v_max_f32_dpp v0, v0, v0 row_shr:2 row_mask:0xf bank_mask:0xf
	v_max_f32_dpp v2, v2, v2 row_shr:2 row_mask:0xf bank_mask:0xf
	s_nop 1
	v_max_f32_dpp v0, v0, v0 row_shr:4 row_mask:0xf bank_mask:0xf
	v_max_f32_dpp v2, v2, v2 row_shr:4 row_mask:0xf bank_mask:0xf
	s_nop 1
	v_max_f32_dpp v0, v0, v0 row_shr:8 row_mask:0xf bank_mask:0xf
	v_max_f32_dpp v2, v2, v2 row_shr:8 row_mask:0xf bank_mask:0xf
	s_nop 1
	v_max_f32_dpp v0, v0, v0 row_bcast:15 row_mask:0xa bank_mask:0xf
	v_max_f32_dpp v2, v2, v2 row_bcast:15 row_mask:0xa bank_mask:0xf
	s_nop 1
	v_max_f32_dpp v0, v0, v0 row_bcast:31 row_mask:0xc bank_mask:0xf
	v_max_f32_dpp v2, v2, v2 row_bcast:31 row_mask:0xc bank_mask:0xf
	s_nop 1
	v_readlane_b32 s100, v0, 63
	v_mov_b32_e32 v81, v82
	v_mov_b32_e32 v80, v2
	s_nop 3
	v_mov_b32_e32 v3, s100
	v_sub_f32_e32 v0, v82, v3
	v_mul_f32_e32 v0, 0x3fb8aa3b, v0
	v_exp_f32_e32 v0, v0
	global_store_dwordx4 v[84:85], v[78:81], off
	ds_write2st64_b32 v134, v79, v80 offset0:192 offset1:193
	ds_write_b32 v134, v0 offset:49664
	s_and_b64 exec, exec, s[44:45]
	s_cbranch_execz .LBB0_633
	v_or_b32_e32 v0, s1, v172
	v_lshlrev_b32_e32 v78, 1, v0
	v_ashrrev_i32_e32 v79, 31, v78
	v_lshl_add_u64 v[78:79], v[78:79], 2, s[22:23]
	v_mov_b32_e32 v2, v77
	global_store_dwordx2 v[78:79], v[2:3], off
